# P3 K-loop: cache-warming dword loads of the next epilogue's new gate tile lines (G_{n+1}, and G_0 at n=0), spread over 4 loop iterations; on top of v58
# baseline (speedup 1.0000x reference)
.LBB0_496:
	s_add_i32 s98, s52, 2
	s_and_b32 s99, s98, 3
	s_cmp_lg_u32 s99, 0
	s_cbranch_scc1 .Lgpf_skip
	s_lshr_b32 s98, s98, 2
	s_lshr_b32 s100, s98, 1
	s_cmp_eq_u32 s100, 0
	s_cbranch_scc1 .Lgpf_next
	s_cmp_lg_u32 s47, 0
	s_cbranch_scc1 .Lgpf_skip
	s_mov_b32 s100, 0
	s_branch .Lgpf_go
.Lgpf_next:
	s_cmp_gt_i32 s47, 2
	s_cbranch_scc1 .Lgpf_skip
	s_mov_b32 s100, 1
.Lgpf_go:
	s_lshl_b32 s99, s49, 8
	s_and_b32 s101, s98, 1
	s_lshl_b32 s101, s101, 7
	s_add_i32 s99, s99, s101
	s_mul_i32 s99, s99, s87
	s_add_i32 s101, s47, s100
	s_lshl_b32 s101, s101, 12
	s_add_i32 s99, s99, s101
	s_lshl_b32 s101, s48, 9
	s_add_i32 s99, s99, s101
	s_add_i32 s99, s99, 0x5000
	s_add_u32 s100, s10, s99
	s_addc_u32 s101, s11, 0
	v_mbcnt_lo_u32_b32 v248, -1, 0
	v_mbcnt_hi_u32_b32 v248, -1, v248
	v_lshrrev_b32_e32 v249, 2, v248
	s_lshr_b32 s98, s83, 2
	v_add_u32_e32 v249, s98, v249
	v_and_b32_e32 v248, 3, v248
	v_lshlrev_b32_e32 v248, 7, v248
	v_mad_u32_u24 v248, v249, s87, v248
	global_load_dword v245, v248, s[100:101]
